# baseline (speedup 1.0000x reference)
; #define LAS __attribute__((address_space(3)))
; __device__ __forceinline__ void pool_units(LAS unsigned char* lds, const bf16* Z, const float* state, const bf16* Wpt, const float* pscale, bf16* MIXIN, int bx, int G, int tid, int wid, int lane) {
;     ...
;         { const int cg8 = tid & 31, r0 = (tid >> 5) * 4;
;           const LAS bf16* up = Ul + cg8 * 8;
;           float sum[8];
; #pragma unroll
;           for (int e = 0; e < 8; ++e) sum[e] = 0.f;
; #pragma unroll
;           for (int i = 1; i < 16; ++i) { float v[8]; unpack8(*(const LAS v4u*)(up + (r0 + 15 - i) * PL_DS), v); const float on = i < w ? 1.f : 0.f;
; #pragma unroll
;               for (int e = 0; e < 8; ++e) sum[e] += on * v[e]; }
; #pragma unroll
;           for (int q = 0; q < 4; ++q) { const int rr = r0 + q; float v[8], vo[8]; unpack8(*(const LAS v4u*)(up + (rr + 15) * PL_DS), v); unpack8(*(const LAS v4u*)(up + (rr + 16 - w) * PL_DS), vo);
.LBB0_124:
	ds_read_b128 v[96:99], v163 offset:7392
	s_lshl_b32 s38, s5, 8
	s_ashr_i32 s4, s4, 2
	s_cmpk_gt_i32 s4, 0xff
	s_cselect_b64 s[50:51], -1, 0
	s_waitcnt lgkmcnt(0)
	v_lshlrev_b32_e32 v3, 16, v97
	v_lshlrev_b32_e32 v2, 16, v96
	v_and_b32_e32 v97, 0xffff0000, v97
	v_and_b32_e32 v96, 0xffff0000, v96
	v_pk_add_f32 v[122:123], v[96:97], 0 op_sel_hi:[1,0]
	v_lshlrev_b32_e32 v97, 16, v99
	v_lshlrev_b32_e32 v96, 16, v98
	v_pk_add_f32 v[148:149], v[96:97], 0 op_sel_hi:[1,0]
	v_and_b32_e32 v97, 0xffff0000, v99
	v_and_b32_e32 v96, 0xffff0000, v98
	v_pk_add_f32 v[150:151], v[96:97], 0 op_sel_hi:[1,0]
	ds_read_b128 v[96:99], v163 offset:6864
	s_lshl_b32 s39, s4, 6
	s_lshl_b32 s4, 2, s5
	s_cmp_eq_u32 s5, 0
	s_cselect_b64 s[12:13], -1, 0
	s_waitcnt lgkmcnt(0)
	v_lshlrev_b32_e32 v171, 16, v97
	v_lshlrev_b32_e32 v170, 16, v96
	v_and_b32_e32 v173, 0xffff0000, v97
	v_and_b32_e32 v172, 0xffff0000, v96
	v_lshlrev_b32_e32 v175, 16, v99
	v_lshlrev_b32_e32 v174, 16, v98
	v_and_b32_e32 v177, 0xffff0000, v99
	v_and_b32_e32 v176, 0xffff0000, v98
	ds_read_b128 v[96:99], v163 offset:6336
	v_pk_add_f32 v[2:3], v[2:3], 0 op_sel_hi:[1,0]
	v_cndmask_b32_e64 v168, 1.0, 0, s[12:13]
	s_cmp_gt_u32 s5, 1
	s_cselect_b64 s[12:13], -1, 0
	s_waitcnt lgkmcnt(0)
	v_lshlrev_b32_e32 v179, 16, v97
	v_lshlrev_b32_e32 v178, 16, v96
	v_and_b32_e32 v183, 0xffff0000, v97
	v_and_b32_e32 v182, 0xffff0000, v96
	v_lshlrev_b32_e32 v185, 16, v99
	v_lshlrev_b32_e32 v184, 16, v98
	v_and_b32_e32 v187, 0xffff0000, v99
	v_and_b32_e32 v186, 0xffff0000, v98
	ds_read_b128 v[96:99], v163 offset:5808
	v_pk_fma_f32 v[2:3], v[168:169], v[170:171], v[2:3] op_sel_hi:[0,1,1]
	v_pk_fma_f32 v[122:123], v[168:169], v[172:173], v[122:123] op_sel_hi:[0,1,1]
	v_cndmask_b32_e64 v214, 0, 1.0, s[12:13]
	v_pk_fma_f32 v[2:3], v[168:169], v[178:179], v[2:3] op_sel_hi:[0,1,1]
	s_waitcnt lgkmcnt(0)
	v_lshlrev_b32_e32 v188, 16, v96
	v_and_b32_e32 v208, 0xffff0000, v96
	v_lshlrev_b32_e32 v189, 16, v97
	v_and_b32_e32 v209, 0xffff0000, v97
	v_lshlrev_b32_e32 v210, 16, v98
	v_and_b32_e32 v212, 0xffff0000, v98
	v_lshlrev_b32_e32 v211, 16, v99
	v_and_b32_e32 v213, 0xffff0000, v99
	ds_read_b128 v[96:99], v163 offset:5280
	ds_read_b128 v[100:103], v163 offset:4752
	ds_read_b128 v[124:127], v163 offset:4224
	ds_read_b128 v[128:131], v163 offset:3696
	v_pk_fma_f32 v[122:123], v[168:169], v[182:183], v[122:123] op_sel_hi:[0,1,1]
	v_pk_fma_f32 v[2:3], v[214:215], v[188:189], v[2:3] op_sel_hi:[0,1,1]
	s_waitcnt lgkmcnt(3)
	v_lshlrev_b32_e32 v171, 16, v97
	v_lshlrev_b32_e32 v170, 16, v96
	v_pk_fma_f32 v[122:123], v[214:215], v[208:209], v[122:123] op_sel_hi:[0,1,1]
	v_and_b32_e32 v97, 0xffff0000, v97
	v_and_b32_e32 v96, 0xffff0000, v96
	s_cmp_eq_u32 s5, 3
	v_pk_fma_f32 v[2:3], v[214:215], v[170:171], v[2:3] op_sel_hi:[0,1,1]
	s_waitcnt lgkmcnt(2)
	v_lshlrev_b32_e32 v171, 16, v101
	v_lshlrev_b32_e32 v170, 16, v100
	v_pk_fma_f32 v[96:97], v[214:215], v[96:97], v[122:123] op_sel_hi:[0,1,1]
	v_and_b32_e32 v101, 0xffff0000, v101
	v_and_b32_e32 v100, 0xffff0000, v100
	s_cselect_b64 s[12:13], -1, 0
	ds_read_b128 v[132:135], v163 offset:3168
	ds_read_b128 v[136:139], v163 offset:2640
	ds_read_b128 v[140:143], v163 offset:2112
	ds_read_b128 v[144:147], v163 offset:1584
	v_pk_fma_f32 v[96:97], v[214:215], v[100:101], v[96:97] op_sel_hi:[0,1,1]
	s_waitcnt lgkmcnt(5)
	v_and_b32_e32 v101, 0xffff0000, v125
	v_and_b32_e32 v100, 0xffff0000, v124
	v_cndmask_b32_e64 v0, 0, 1.0, s[12:13]
	v_pk_fma_f32 v[96:97], v[214:215], v[100:101], v[96:97] op_sel_hi:[0,1,1]
	s_waitcnt lgkmcnt(4)
	v_and_b32_e32 v101, 0xffff0000, v129
	v_and_b32_e32 v100, 0xffff0000, v128
	v_pk_fma_f32 v[96:97], v[0:1], v[100:101], v[96:97] op_sel_hi:[0,1,1]
	s_waitcnt lgkmcnt(3)
	v_and_b32_e32 v101, 0xffff0000, v133
	v_and_b32_e32 v100, 0xffff0000, v132
	v_pk_fma_f32 v[96:97], v[0:1], v[100:101], v[96:97] op_sel_hi:[0,1,1]
	s_waitcnt lgkmcnt(2)
	v_and_b32_e32 v101, 0xffff0000, v137
	v_and_b32_e32 v100, 0xffff0000, v136
	v_pk_fma_f32 v[96:97], v[0:1], v[100:101], v[96:97] op_sel_hi:[0,1,1]
	s_waitcnt lgkmcnt(1)
	v_and_b32_e32 v101, 0xffff0000, v141
	v_and_b32_e32 v100, 0xffff0000, v140
	v_pk_fma_f32 v[96:97], v[0:1], v[100:101], v[96:97] op_sel_hi:[0,1,1]
	s_waitcnt lgkmcnt(0)
	v_and_b32_e32 v101, 0xffff0000, v145
	v_and_b32_e32 v100, 0xffff0000, v144
	v_pk_fma_f32 v[122:123], v[0:1], v[100:101], v[96:97] op_sel_hi:[0,1,1]
	v_pk_fma_f32 v[96:97], v[168:169], v[174:175], v[148:149] op_sel_hi:[0,1,1]
	v_pk_fma_f32 v[96:97], v[168:169], v[184:185], v[96:97] op_sel_hi:[0,1,1]
	v_pk_fma_f32 v[96:97], v[214:215], v[210:211], v[96:97] op_sel_hi:[0,1,1]
	v_lshlrev_b32_e32 v101, 16, v99
	v_lshlrev_b32_e32 v100, 16, v98
	v_pk_fma_f32 v[96:97], v[214:215], v[100:101], v[96:97] op_sel_hi:[0,1,1]
	v_lshlrev_b32_e32 v101, 16, v103
	v_lshlrev_b32_e32 v100, 16, v102
	v_pk_fma_f32 v[96:97], v[214:215], v[100:101], v[96:97] op_sel_hi:[0,1,1]
	v_lshlrev_b32_e32 v101, 16, v127
	v_lshlrev_b32_e32 v100, 16, v126
	v_pk_fma_f32 v[96:97], v[214:215], v[100:101], v[96:97] op_sel_hi:[0,1,1]
	v_lshlrev_b32_e32 v101, 16, v131
	v_lshlrev_b32_e32 v100, 16, v130
	v_pk_fma_f32 v[96:97], v[0:1], v[100:101], v[96:97] op_sel_hi:[0,1,1]
	v_lshlrev_b32_e32 v101, 16, v135
	v_lshlrev_b32_e32 v100, 16, v134
	v_pk_fma_f32 v[96:97], v[0:1], v[100:101], v[96:97] op_sel_hi:[0,1,1]
	v_lshlrev_b32_e32 v101, 16, v139
	v_lshlrev_b32_e32 v100, 16, v138
	v_pk_fma_f32 v[96:97], v[0:1], v[100:101], v[96:97] op_sel_hi:[0,1,1]
	v_lshlrev_b32_e32 v101, 16, v143
	v_lshlrev_b32_e32 v100, 16, v142
	v_pk_fma_f32 v[96:97], v[0:1], v[100:101], v[96:97] op_sel_hi:[0,1,1]
	v_lshlrev_b32_e32 v101, 16, v147
	v_lshlrev_b32_e32 v100, 16, v146
; #define LAS __attribute__((address_space(3)))
; __device__ __forceinline__ unsigned pk2(float lo, float hi) { return f2bf(lo) | (f2bf(hi) << 16); }
; __device__ __forceinline__ void pool_units(LAS unsigned char* lds, const bf16* Z, const float* state, const bf16* Wpt, const float* pscale, bf16* MIXIN, int bx, int G, int tid, int wid, int lane) {
;     ...
;           for (int i = 1; i < 16; ++i) { float v[8]; unpack8(*(const LAS v4u*)(up + (r0 + 15 - i) * PL_DS), v); const float on = i < w ? 1.f : 0.f;
; #pragma unroll
;               for (int e = 0; e < 8; ++e) sum[e] += on * v[e]; }
; #pragma unroll
;           for (int q = 0; q < 4; ++q) { const int rr = r0 + q; float v[8], vo[8]; unpack8(*(const LAS v4u*)(up + (rr + 15) * PL_DS), v); unpack8(*(const LAS v4u*)(up + (rr + 16 - w) * PL_DS), vo);
;               const int pos1 = sample ? w : (c * 64 + rr + 1); const float icnt = 1.0f / (float)(pos1 < w ? pos1 : w);
;               float d[8];
; #pragma unroll
;               for (int e = 0; e < 8; ++e) { sum[e] += v[e]; d[e] = sum[e] * icnt - v[e]; sum[e] -= vo[e]; }
;               v4u o; o.x = pk2(d[0], d[1]); o.y = pk2(d[2], d[3]); o.z = pk2(d[4], d[5]); o.w = pk2(d[6], d[7]);
;               *(LAS v4u*)(Dl + rr * PL_DS + cg8 * 8) = o; }
	v_pk_fma_f32 v[2:3], v[214:215], v[170:171], v[2:3] op_sel_hi:[0,1,1]
	v_lshlrev_b32_e32 v171, 16, v125
	v_lshlrev_b32_e32 v170, 16, v124
	v_pk_fma_f32 v[124:125], v[0:1], v[100:101], v[96:97] op_sel_hi:[0,1,1]
	v_pk_fma_f32 v[96:97], v[168:169], v[176:177], v[150:151] op_sel_hi:[0,1,1]
	v_pk_fma_f32 v[96:97], v[168:169], v[186:187], v[96:97] op_sel_hi:[0,1,1]
	v_pk_fma_f32 v[96:97], v[214:215], v[212:213], v[96:97] op_sel_hi:[0,1,1]
	v_and_b32_e32 v99, 0xffff0000, v99
	v_and_b32_e32 v98, 0xffff0000, v98
	v_pk_fma_f32 v[96:97], v[214:215], v[98:99], v[96:97] op_sel_hi:[0,1,1]
	v_and_b32_e32 v99, 0xffff0000, v103
	v_and_b32_e32 v98, 0xffff0000, v102
	v_pk_fma_f32 v[96:97], v[214:215], v[98:99], v[96:97] op_sel_hi:[0,1,1]
	v_and_b32_e32 v99, 0xffff0000, v127
	v_and_b32_e32 v98, 0xffff0000, v126
	v_pk_fma_f32 v[96:97], v[214:215], v[98:99], v[96:97] op_sel_hi:[0,1,1]
	v_and_b32_e32 v99, 0xffff0000, v131
	v_and_b32_e32 v98, 0xffff0000, v130
	v_pk_fma_f32 v[96:97], v[0:1], v[98:99], v[96:97] op_sel_hi:[0,1,1]
	v_and_b32_e32 v99, 0xffff0000, v135
	v_and_b32_e32 v98, 0xffff0000, v134
	v_pk_fma_f32 v[96:97], v[0:1], v[98:99], v[96:97] op_sel_hi:[0,1,1]
	v_and_b32_e32 v99, 0xffff0000, v139
	v_and_b32_e32 v98, 0xffff0000, v138
	s_and_b32 s5, s39, 0x7c0
	v_pk_fma_f32 v[96:97], v[0:1], v[98:99], v[96:97] op_sel_hi:[0,1,1]
	v_and_b32_e32 v99, 0xffff0000, v143
	v_and_b32_e32 v98, 0xffff0000, v142
	s_or_b32 s5, s5, 1
	v_pk_fma_f32 v[96:97], v[0:1], v[98:99], v[96:97] op_sel_hi:[0,1,1]
	v_and_b32_e32 v99, 0xffff0000, v147
	v_and_b32_e32 v98, 0xffff0000, v146
	v_add_u32_e32 v167, s5, v158
	v_pk_fma_f32 v[126:127], v[0:1], v[98:99], v[96:97] op_sel_hi:[0,1,1]
	ds_read_b128 v[96:99], v163 offset:1056
	v_min_i32_e32 v168, s4, v167
	v_mov_b32_e32 v167, s4
	v_cndmask_b32_e64 v168, v168, v167, s[50:51]
	v_pk_fma_f32 v[2:3], v[214:215], v[170:171], v[2:3] op_sel_hi:[0,1,1]
	v_lshlrev_b32_e32 v171, 16, v129
	v_lshlrev_b32_e32 v170, 16, v128
	v_cvt_f32_i32_e32 v168, v168
	v_pk_fma_f32 v[2:3], v[0:1], v[170:171], v[2:3] op_sel_hi:[0,1,1]
	v_lshlrev_b32_e32 v171, 16, v133
	v_lshlrev_b32_e32 v170, 16, v132
	v_pk_fma_f32 v[2:3], v[0:1], v[170:171], v[2:3] op_sel_hi:[0,1,1]
	v_lshlrev_b32_e32 v171, 16, v137
	v_lshlrev_b32_e32 v170, 16, v136
	v_pk_fma_f32 v[2:3], v[0:1], v[170:171], v[2:3] op_sel_hi:[0,1,1]
	v_lshlrev_b32_e32 v171, 16, v141
	v_lshlrev_b32_e32 v170, 16, v140
	s_waitcnt lgkmcnt(0)
	v_lshlrev_b32_e32 v141, 16, v97
	v_lshlrev_b32_e32 v140, 16, v96
	v_and_b32_e32 v143, 0xffff0000, v97
	v_and_b32_e32 v142, 0xffff0000, v96
	v_lshlrev_b32_e32 v129, 16, v99
	v_lshlrev_b32_e32 v128, 16, v98
	v_and_b32_e32 v131, 0xffff0000, v99
	v_and_b32_e32 v130, 0xffff0000, v98
	ds_read_b128 v[96:99], v163 offset:528
	v_pk_fma_f32 v[2:3], v[0:1], v[170:171], v[2:3] op_sel_hi:[0,1,1]
	v_lshlrev_b32_e32 v171, 16, v145
	v_lshlrev_b32_e32 v170, 16, v144
	v_div_scale_f32 v169, s[12:13], v168, v168, 1.0
	v_pk_fma_f32 v[2:3], v[0:1], v[170:171], v[2:3] op_sel_hi:[0,1,1]
	v_rcp_f32_e32 v170, v169
	s_waitcnt lgkmcnt(0)
	v_lshlrev_b32_e32 v145, 16, v97
	v_lshlrev_b32_e32 v144, 16, v96
	v_and_b32_e32 v147, 0xffff0000, v97
	v_and_b32_e32 v146, 0xffff0000, v96
	v_lshlrev_b32_e32 v133, 16, v99
	v_lshlrev_b32_e32 v132, 16, v98
	v_and_b32_e32 v135, 0xffff0000, v99
	v_and_b32_e32 v134, 0xffff0000, v98
	ds_read_b128 v[96:99], v163
	v_fma_f32 v171, -v169, v170, 1.0
	ds_read_b128 v[100:103], v163 offset:7920
	v_fmac_f32_e32 v170, v171, v170
	v_div_scale_f32 v171, vcc, 1.0, v168, 1.0
	v_mul_f32_e32 v172, v171, v170
	v_fma_f32 v173, -v169, v172, v171
	s_waitcnt lgkmcnt(1)
	v_lshlrev_b32_e32 v150, 16, v96
	v_and_b32_e32 v148, 0xffff0000, v96
	v_subrev_u32_e32 v96, s4, v158
	v_fmac_f32_e32 v172, v173, v170
	v_pk_fma_f32 v[122:123], v[0:1], v[142:143], v[122:123] op_sel_hi:[0,1,1]
	v_pk_fma_f32 v[126:127], v[0:1], v[130:131], v[126:127] op_sel_hi:[0,1,1]
	v_lshlrev_b32_e32 v151, 16, v97
	v_and_b32_e32 v149, 0xffff0000, v97
	v_and_b32_e32 v136, 0xffff0000, v98
	v_and_b32_e32 v137, 0xffff0000, v99
	v_mad_u64_u32 v[96:97], s[12:13], v96, s91, v[106:107]
	v_fma_f32 v169, -v169, v172, v171
	v_pk_fma_f32 v[2:3], v[0:1], v[140:141], v[2:3] op_sel_hi:[0,1,1]
	v_pk_fma_f32 v[122:123], v[0:1], v[146:147], v[122:123] op_sel_hi:[0,1,1]
	v_pk_fma_f32 v[124:125], v[0:1], v[128:129], v[124:125] op_sel_hi:[0,1,1]
	v_pk_fma_f32 v[126:127], v[0:1], v[134:135], v[126:127] op_sel_hi:[0,1,1]
	v_lshlrev_b32_e32 v138, 16, v98
	v_lshlrev_b32_e32 v139, 16, v99
	ds_read_b128 v[96:99], v96 offset:8448
	v_div_fmas_f32 v169, v169, v170, v172
	v_pk_fma_f32 v[2:3], v[0:1], v[144:145], v[2:3] op_sel_hi:[0,1,1]
	v_pk_fma_f32 v[122:123], v[0:1], v[148:149], v[122:123] op_sel_hi:[0,1,1]
	s_waitcnt lgkmcnt(1)
; #define LAS __attribute__((address_space(3)))
; __device__ __forceinline__ unsigned pk2(float lo, float hi) { return f2bf(lo) | (f2bf(hi) << 16); }
; __device__ __forceinline__ void pool_units(LAS unsigned char* lds, const bf16* Z, const float* state, const bf16* Wpt, const float* pscale, bf16* MIXIN, int bx, int G, int tid, int wid, int lane) {
;     ...
;           for (int i = 1; i < 16; ++i) { float v[8]; unpack8(*(const LAS v4u*)(up + (r0 + 15 - i) * PL_DS), v); const float on = i < w ? 1.f : 0.f;
; #pragma unroll
;               for (int e = 0; e < 8; ++e) sum[e] += on * v[e]; }
; #pragma unroll
;           for (int q = 0; q < 4; ++q) { const int rr = r0 + q; float v[8], vo[8]; unpack8(*(const LAS v4u*)(up + (rr + 15) * PL_DS), v); unpack8(*(const LAS v4u*)(up + (rr + 16 - w) * PL_DS), vo);
;               const int pos1 = sample ? w : (c * 64 + rr + 1); const float icnt = 1.0f / (float)(pos1 < w ? pos1 : w);
;               float d[8];
; #pragma unroll
;               for (int e = 0; e < 8; ++e) { sum[e] += v[e]; d[e] = sum[e] * icnt - v[e]; sum[e] -= vo[e]; }
;               v4u o; o.x = pk2(d[0], d[1]); o.y = pk2(d[2], d[3]); o.z = pk2(d[4], d[5]); o.w = pk2(d[6], d[7]);
;               *(LAS v4u*)(Dl + rr * PL_DS + cg8 * 8) = o; }
	v_lshlrev_b32_e32 v141, 16, v101
	v_lshlrev_b32_e32 v140, 16, v100
	v_and_b32_e32 v101, 0xffff0000, v101
	v_and_b32_e32 v100, 0xffff0000, v100
	v_pk_fma_f32 v[124:125], v[0:1], v[132:133], v[124:125] op_sel_hi:[0,1,1]
	v_pk_fma_f32 v[126:127], v[0:1], v[136:137], v[126:127] op_sel_hi:[0,1,1]
	v_lshlrev_b32_e32 v129, 16, v103
	v_lshlrev_b32_e32 v128, 16, v102
	v_and_b32_e32 v103, 0xffff0000, v103
	v_and_b32_e32 v102, 0xffff0000, v102
	v_div_fixup_f32 v168, v169, v168, 1.0
	v_pk_fma_f32 v[2:3], v[0:1], v[150:151], v[2:3] op_sel_hi:[0,1,1]
	v_pk_add_f32 v[122:123], v[122:123], v[100:101]
	v_pk_fma_f32 v[124:125], v[0:1], v[138:139], v[124:125] op_sel_hi:[0,1,1]
	v_pk_add_f32 v[130:131], v[126:127], v[102:103]
	v_pk_add_f32 v[2:3], v[2:3], v[140:141]
	v_pk_fma_f32 v[100:101], v[168:169], v[122:123], v[100:101] op_sel_hi:[0,1,1] neg_lo:[0,0,1] neg_hi:[0,0,1]
	v_pk_add_f32 v[124:125], v[124:125], v[128:129]
	v_pk_fma_f32 v[102:103], v[168:169], v[130:131], v[102:103] op_sel_hi:[0,1,1] neg_lo:[0,0,1] neg_hi:[0,0,1]
	v_pk_fma_f32 v[140:141], v[168:169], v[2:3], v[140:141] op_sel_hi:[0,1,1] neg_lo:[0,0,1] neg_hi:[0,0,1]
	v_pk_fma_f32 v[126:127], v[168:169], v[124:125], v[128:129] op_sel_hi:[0,1,1] neg_lo:[0,0,1] neg_hi:[0,0,1]
	v_bfe_u32 v0, v103, 16, 1
	v_bfe_u32 v132, v100, 16, 1
	v_bfe_u32 v129, v101, 16, 1
	v_add3_u32 v100, v100, v132, s84
	v_add3_u32 v0, v103, v0, s84
	v_bfe_u32 v103, v140, 16, 1
	v_bfe_u32 v132, v127, 16, 1
	v_add3_u32 v101, v101, v129, s84
	v_bfe_u32 v129, v126, 16, 1
	v_add3_u32 v127, v127, v132, s84
	v_add3_u32 v103, v140, v103, s84
	v_bfe_u32 v128, v102, 16, 1
	v_add3_u32 v126, v126, v129, s84
	v_lshrrev_b32_e32 v129, 16, v103
	v_lshrrev_b32_e32 v103, 16, v127
	v_add3_u32 v102, v102, v128, s84
	v_lshrrev_b32_e32 v126, 16, v126
	v_and_or_b32 v103, v0, s85, v103
	v_subrev_u32_e32 v0, s4, v160
	v_and_or_b32 v102, v102, s85, v126
	v_mad_u64_u32 v[126:127], s[12:13], v0, s91, v[106:107]
	v_add_u32_e32 v0, s5, v160
	v_min_i32_e32 v0, s4, v0
	v_cndmask_b32_e64 v0, v0, v167, s[50:51]
	v_cvt_f32_i32_e32 v0, v0
	v_bfe_u32 v128, v141, 16, 1
	v_add3_u32 v128, v141, v128, s84
	v_lshrrev_b32_e32 v128, 16, v128
	v_div_scale_f32 v132, s[12:13], v0, v0, 1.0
	v_rcp_f32_e32 v133, v132
	v_and_or_b32 v101, v101, s85, v128
	v_and_or_b32 v100, v100, s85, v129
	ds_write_b128 v163, v[100:103] offset:41984
	v_fma_f32 v134, -v132, v133, 1.0
	v_fmac_f32_e32 v133, v134, v133
	v_div_scale_f32 v134, vcc, 1.0, v0, 1.0
	v_mul_f32_e32 v135, v134, v133
	ds_read_b128 v[100:103], v164 offset:7920
	ds_read_b128 v[126:129], v126 offset:8448
	v_fma_f32 v136, -v132, v135, v134
	v_fmac_f32_e32 v135, v136, v133
	v_fma_f32 v132, -v132, v135, v134
	v_div_fmas_f32 v132, v132, v133, v135
	v_div_fixup_f32 v0, v132, v0, 1.0
	s_waitcnt lgkmcnt(3)
	v_lshlrev_b32_e32 v133, 16, v97
	v_lshlrev_b32_e32 v132, 16, v96
	v_and_b32_e32 v97, 0xffff0000, v97
	v_and_b32_e32 v96, 0xffff0000, v96
	v_pk_add_f32 v[2:3], v[2:3], v[132:133] neg_lo:[0,1] neg_hi:[0,1]
	v_pk_add_f32 v[96:97], v[122:123], v[96:97] neg_lo:[0,1] neg_hi:[0,1]
	s_waitcnt lgkmcnt(1)
	v_lshlrev_b32_e32 v123, 16, v101
	v_lshlrev_b32_e32 v122, 16, v100
	v_and_b32_e32 v101, 0xffff0000, v101
	v_and_b32_e32 v100, 0xffff0000, v100
	v_pk_add_f32 v[2:3], v[2:3], v[122:123]
	v_pk_add_f32 v[132:133], v[96:97], v[100:101]
	v_pk_fma_f32 v[96:97], v[0:1], v[2:3], v[122:123] op_sel_hi:[0,1,1] neg_lo:[0,0,1] neg_hi:[0,0,1]
	v_lshlrev_b32_e32 v123, 16, v99
	v_lshlrev_b32_e32 v122, 16, v98
	v_and_b32_e32 v99, 0xffff0000, v99
	v_and_b32_e32 v98, 0xffff0000, v98
	v_pk_add_f32 v[122:123], v[124:125], v[122:123] neg_lo:[0,1] neg_hi:[0,1]
	v_pk_add_f32 v[98:99], v[130:131], v[98:99] neg_lo:[0,1] neg_hi:[0,1]
	v_lshlrev_b32_e32 v125, 16, v103
	v_lshlrev_b32_e32 v124, 16, v102
	v_and_b32_e32 v103, 0xffff0000, v103
	v_and_b32_e32 v102, 0xffff0000, v102
	v_pk_add_f32 v[130:131], v[98:99], v[102:103]
	v_pk_fma_f32 v[100:101], v[0:1], v[132:133], v[100:101] op_sel_hi:[0,1,1] neg_lo:[0,0,1] neg_hi:[0,0,1]
	v_pk_add_f32 v[122:123], v[122:123], v[124:125]
	v_pk_fma_f32 v[102:103], v[0:1], v[130:131], v[102:103] op_sel_hi:[0,1,1] neg_lo:[0,0,1] neg_hi:[0,0,1]
	v_pk_fma_f32 v[98:99], v[0:1], v[122:123], v[124:125] op_sel_hi:[0,1,1] neg_lo:[0,0,1] neg_hi:[0,0,1]
	v_bfe_u32 v0, v103, 16, 1
	v_bfe_u32 v124, v102, 16, 1
	v_bfe_u32 v125, v101, 16, 1
	v_bfe_u32 v134, v100, 16, 1
	v_add3_u32 v100, v100, v134, s84
	v_add3_u32 v101, v101, v125, s84
	v_add3_u32 v102, v102, v124, s84
	v_add3_u32 v0, v103, v0, s84
	v_bfe_u32 v103, v96, 16, 1
	v_bfe_u32 v124, v97, 16, 1
	v_bfe_u32 v125, v98, 16, 1
	v_bfe_u32 v134, v99, 16, 1
	v_add3_u32 v99, v99, v134, s84
	v_add3_u32 v98, v98, v125, s84
	v_add3_u32 v97, v97, v124, s84
	v_add3_u32 v96, v96, v103, s84
	v_lshrrev_b32_e32 v96, 16, v96
	v_lshrrev_b32_e32 v97, 16, v97
	v_lshrrev_b32_e32 v98, 16, v98
	v_lshrrev_b32_e32 v99, 16, v99
	v_and_or_b32 v99, v0, s85, v99
	v_and_or_b32 v98, v102, s85, v98
	v_and_or_b32 v97, v101, s85, v97
	v_and_or_b32 v96, v100, s85, v96
	v_subrev_u32_e32 v0, s4, v161
	ds_write_b128 v164, v[96:99] offset:41984
	v_mad_u64_u32 v[96:97], s[12:13], v0, s91, v[106:107]
	v_add_u32_e32 v0, s5, v161
	v_min_i32_e32 v0, s4, v0
	v_cndmask_b32_e64 v0, v0, v167, s[50:51]
	v_cvt_f32_i32_e32 v0, v0
	ds_read_b128 v[100:103], v164 offset:8448
	ds_read_b128 v[96:99], v96 offset:8448
	s_add_i32 s11, s11, s60
	v_div_scale_f32 v124, s[12:13], v0, v0, 1.0
	v_rcp_f32_e32 v125, v124
	s_nop 0
	v_fma_f32 v134, -v124, v125, 1.0
	v_fmac_f32_e32 v125, v134, v125
	v_div_scale_f32 v134, vcc, 1.0, v0, 1.0
	v_mul_f32_e32 v135, v134, v125
	v_fma_f32 v136, -v124, v135, v134
	v_fmac_f32_e32 v135, v136, v125
	v_fma_f32 v124, -v124, v135, v134
	v_div_fmas_f32 v124, v124, v125, v135
	v_div_fixup_f32 v0, v124, v0, 1.0
	s_waitcnt lgkmcnt(3)
; #define LAS __attribute__((address_space(3)))
; __device__ __forceinline__ unsigned pk2(float lo, float hi) { return f2bf(lo) | (f2bf(hi) << 16); }
; __device__ __forceinline__ void pool_units(LAS unsigned char* lds, const bf16* Z, const float* state, const bf16* Wpt, const float* pscale, bf16* MIXIN, int bx, int G, int tid, int wid, int lane) {
;     ...
;           for (int q = 0; q < 4; ++q) { const int rr = r0 + q; float v[8], vo[8]; unpack8(*(const LAS v4u*)(up + (rr + 15) * PL_DS), v); unpack8(*(const LAS v4u*)(up + (rr + 16 - w) * PL_DS), vo);
;               const int pos1 = sample ? w : (c * 64 + rr + 1); const float icnt = 1.0f / (float)(pos1 < w ? pos1 : w);
;               float d[8];
; #pragma unroll
;               for (int e = 0; e < 8; ++e) { sum[e] += v[e]; d[e] = sum[e] * icnt - v[e]; sum[e] -= vo[e]; }
;               v4u o; o.x = pk2(d[0], d[1]); o.y = pk2(d[2], d[3]); o.z = pk2(d[4], d[5]); o.w = pk2(d[6], d[7]);
;               *(LAS v4u*)(Dl + rr * PL_DS + cg8 * 8) = o; }
;         }
;         __syncthreads();
	v_lshlrev_b32_e32 v125, 16, v127
	v_lshlrev_b32_e32 v124, 16, v126
	v_and_b32_e32 v127, 0xffff0000, v127
	v_and_b32_e32 v126, 0xffff0000, v126
	v_pk_add_f32 v[2:3], v[2:3], v[124:125] neg_lo:[0,1] neg_hi:[0,1]
	v_pk_add_f32 v[126:127], v[132:133], v[126:127] neg_lo:[0,1] neg_hi:[0,1]
	s_waitcnt lgkmcnt(1)
	v_lshlrev_b32_e32 v133, 16, v101
	v_lshlrev_b32_e32 v132, 16, v100
	v_pk_add_f32 v[124:125], v[2:3], v[132:133]
	v_lshlrev_b32_e32 v3, 16, v129
	v_lshlrev_b32_e32 v2, 16, v128
	v_and_b32_e32 v129, 0xffff0000, v129
	v_and_b32_e32 v128, 0xffff0000, v128
	v_and_b32_e32 v101, 0xffff0000, v101
	v_and_b32_e32 v100, 0xffff0000, v100
	v_pk_add_f32 v[2:3], v[122:123], v[2:3] neg_lo:[0,1] neg_hi:[0,1]
	v_pk_add_f32 v[122:123], v[130:131], v[128:129] neg_lo:[0,1] neg_hi:[0,1]
	v_lshlrev_b32_e32 v129, 16, v103
	v_lshlrev_b32_e32 v128, 16, v102
	v_and_b32_e32 v103, 0xffff0000, v103
	v_and_b32_e32 v102, 0xffff0000, v102
	v_pk_add_f32 v[126:127], v[126:127], v[100:101]
	v_pk_add_f32 v[122:123], v[122:123], v[102:103]
	v_pk_fma_f32 v[100:101], v[0:1], v[126:127], v[100:101] op_sel_hi:[0,1,1] neg_lo:[0,0,1] neg_hi:[0,0,1]
	v_pk_add_f32 v[2:3], v[2:3], v[128:129]
	v_pk_fma_f32 v[102:103], v[0:1], v[122:123], v[102:103] op_sel_hi:[0,1,1] neg_lo:[0,0,1] neg_hi:[0,0,1]
	v_pk_fma_f32 v[132:133], v[0:1], v[124:125], v[132:133] op_sel_hi:[0,1,1] neg_lo:[0,0,1] neg_hi:[0,0,1]
	v_pk_fma_f32 v[128:129], v[0:1], v[2:3], v[128:129] op_sel_hi:[0,1,1] neg_lo:[0,0,1] neg_hi:[0,0,1]
	v_bfe_u32 v0, v103, 16, 1
	v_bfe_u32 v134, v100, 16, 1
	v_bfe_u32 v131, v101, 16, 1
	v_add3_u32 v100, v100, v134, s84
	v_add3_u32 v0, v103, v0, s84
	v_bfe_u32 v103, v132, 16, 1
	v_bfe_u32 v134, v129, 16, 1
	v_add3_u32 v101, v101, v131, s84
	v_bfe_u32 v131, v128, 16, 1
	v_add3_u32 v129, v129, v134, s84
	v_add3_u32 v103, v132, v103, s84
	v_add3_u32 v128, v128, v131, s84
	v_lshrrev_b32_e32 v131, 16, v103
	v_lshrrev_b32_e32 v103, 16, v129
	v_and_or_b32 v103, v0, s85, v103
	v_add_u32_e32 v0, s5, v162
	v_min_i32_e32 v0, s4, v0
	v_cndmask_b32_e64 v0, v0, v167, s[50:51]
	v_cvt_f32_i32_e32 v0, v0
	v_bfe_u32 v130, v102, 16, 1
	v_add3_u32 v102, v102, v130, s84
	v_lshrrev_b32_e32 v128, 16, v128
	v_and_or_b32 v102, v102, s85, v128
	v_div_scale_f32 v128, s[4:5], v0, v0, 1.0
	v_rcp_f32_e32 v129, v128
	v_bfe_u32 v130, v133, 16, 1
	v_add3_u32 v130, v133, v130, s84
	v_lshrrev_b32_e32 v130, 16, v130
	v_and_or_b32 v101, v101, s85, v130
	v_fma_f32 v130, -v128, v129, 1.0
	v_fmac_f32_e32 v129, v130, v129
	v_div_scale_f32 v130, vcc, 1.0, v0, 1.0
	v_and_or_b32 v100, v100, s85, v131
	v_mul_f32_e32 v131, v130, v129
	ds_write_b128 v164, v[100:103] offset:42512
	ds_read_b128 v[100:103], v164 offset:8976
	v_fma_f32 v132, -v128, v131, v130
	v_fmac_f32_e32 v131, v132, v129
	v_fma_f32 v128, -v128, v131, v130
	v_div_fmas_f32 v128, v128, v129, v131
	v_div_fixup_f32 v0, v128, v0, 1.0
	s_waitcnt lgkmcnt(2)
	v_lshlrev_b32_e32 v129, 16, v97
	v_lshlrev_b32_e32 v128, 16, v96
	v_and_b32_e32 v97, 0xffff0000, v97
	v_and_b32_e32 v96, 0xffff0000, v96
	v_pk_add_f32 v[96:97], v[126:127], v[96:97] neg_lo:[0,1] neg_hi:[0,1]
	s_waitcnt lgkmcnt(0)
	v_lshlrev_b32_e32 v127, 16, v101
	v_lshlrev_b32_e32 v126, 16, v100
	v_and_b32_e32 v101, 0xffff0000, v101
	v_and_b32_e32 v100, 0xffff0000, v100
	v_pk_add_f32 v[96:97], v[96:97], v[100:101]
	v_pk_add_f32 v[124:125], v[124:125], v[128:129] neg_lo:[0,1] neg_hi:[0,1]
	v_pk_fma_f32 v[96:97], v[0:1], v[96:97], v[100:101] op_sel_hi:[0,1,1] neg_lo:[0,0,1] neg_hi:[0,0,1]
	v_lshlrev_b32_e32 v101, 16, v99
	v_lshlrev_b32_e32 v100, 16, v98
	v_and_b32_e32 v99, 0xffff0000, v99
	v_and_b32_e32 v98, 0xffff0000, v98
	v_pk_add_f32 v[2:3], v[2:3], v[100:101] neg_lo:[0,1] neg_hi:[0,1]
	v_pk_add_f32 v[98:99], v[122:123], v[98:99] neg_lo:[0,1] neg_hi:[0,1]
	v_lshlrev_b32_e32 v101, 16, v103
	v_lshlrev_b32_e32 v100, 16, v102
	v_and_b32_e32 v103, 0xffff0000, v103
	v_and_b32_e32 v102, 0xffff0000, v102
	v_pk_add_f32 v[98:99], v[98:99], v[102:103]
	v_pk_add_f32 v[124:125], v[124:125], v[126:127]
	v_pk_add_f32 v[2:3], v[2:3], v[100:101]
	v_pk_fma_f32 v[98:99], v[0:1], v[98:99], v[102:103] op_sel_hi:[0,1,1] neg_lo:[0,0,1] neg_hi:[0,0,1]
	v_pk_fma_f32 v[124:125], v[0:1], v[124:125], v[126:127] op_sel_hi:[0,1,1] neg_lo:[0,0,1] neg_hi:[0,0,1]
	v_pk_fma_f32 v[2:3], v[0:1], v[2:3], v[100:101] op_sel_hi:[0,1,1] neg_lo:[0,0,1] neg_hi:[0,0,1]
	v_bfe_u32 v0, v99, 16, 1
	v_bfe_u32 v100, v98, 16, 1
	v_bfe_u32 v101, v97, 16, 1
	v_bfe_u32 v102, v96, 16, 1
	v_add3_u32 v96, v96, v102, s84
	v_add3_u32 v97, v97, v101, s84
	v_add3_u32 v98, v98, v100, s84
	v_add3_u32 v0, v99, v0, s84
	v_bfe_u32 v99, v124, 16, 1
	v_bfe_u32 v100, v125, 16, 1
	v_bfe_u32 v101, v2, 16, 1
	v_bfe_u32 v102, v3, 16, 1
	v_add3_u32 v3, v3, v102, s84
	v_add3_u32 v2, v2, v101, s84
	v_add3_u32 v100, v125, v100, s84
	v_add3_u32 v99, v124, v99, s84
	v_lshrrev_b32_e32 v101, 16, v99
	v_lshrrev_b32_e32 v100, 16, v100
	v_lshrrev_b32_e32 v2, 16, v2
	v_lshrrev_b32_e32 v3, 16, v3
	v_and_or_b32 v99, v0, s85, v3
	v_and_or_b32 v98, v98, s85, v2
	v_and_or_b32 v97, v97, s85, v100
	v_and_or_b32 v96, v96, s85, v101
	ds_write_b128 v164, v[96:99] offset:43040
	s_waitcnt lgkmcnt(0)
	s_barrier
; #define LAS __attribute__((address_space(3)))
; #define MFMA16(a, b, c) __builtin_amdgcn_mfma_f32_16x16x32_bf16((a), (b), (c), 0, 0, 0)
; __device__ __forceinline__ void pool_units(LAS unsigned char* lds, const bf16* Z, const float* state, const bf16* Wpt, const float* pscale, bf16* MIXIN, int bx, int G, int tid, int wid, int lane) {
;     ...
;         f32x4 acc[2][4];
; #pragma unroll
;         for (int nt = 0; nt < 2; ++nt)
; #pragma unroll
;             for (int m = 0; m < 4; ++m) acc[nt][m] = (f32x4){0.f, 0.f, 0.f, 0.f};
; #pragma unroll
;         for (int ks = 0; ks < 8; ++ks) {
;             bf16x8 db[4];
; #pragma unroll
;             for (int m = 0; m < 4; ++m) db[m] = *(const LAS bf16x8*)(Dl + (m * 16 + fr) * PL_DS + ks * 32 + fq * 8);
; #pragma unroll
;             for (int nt = 0; nt < 2; ++nt)
; #pragma unroll
;                 for (int m = 0; m < 4; ++m) acc[nt][m] = MFMA16(wa[ks][nt], db[m], acc[nt][m]);
;         }
	ds_read_b128 v[96:99], v165 offset:41984
	ds_read_b128 v[100:103], v165 offset:50432
	ds_read_b128 v[122:125], v165 offset:58880
	ds_read_b128 v[126:129], v166 offset:41984
	s_waitcnt vmcnt(17) lgkmcnt(3)
	v_mfma_f32_16x16x32_bf16 v[130:133], v[216:219], v[96:99], 0
	v_add_u32_e32 v2, s38, v159
	v_ashrrev_i32_e32 v3, 31, v2
	v_lshl_add_u64 v[2:3], v[2:3], 1, s[16:17]
	s_waitcnt lgkmcnt(2)
	v_mfma_f32_16x16x32_bf16 v[134:137], v[216:219], v[100:103], 0
	s_andn2_b64 vcc, exec, s[96:97]
	s_mov_b32 s4, s61
	s_waitcnt lgkmcnt(1)
	v_mfma_f32_16x16x32_bf16 v[138:141], v[216:219], v[122:125], 0
	s_waitcnt lgkmcnt(0)
	v_mfma_f32_16x16x32_bf16 v[88:91], v[216:219], v[126:129], 0
	s_waitcnt vmcnt(15)
	v_mfma_f32_16x16x32_bf16 v[96:99], v[224:227], v[96:99], 0
	v_mfma_f32_16x16x32_bf16 v[100:103], v[224:227], v[100:103], 0
	v_mfma_f32_16x16x32_bf16 v[122:125], v[224:227], v[122:125], 0
	v_mfma_f32_16x16x32_bf16 v[92:95], v[224:227], v[126:129], 0
	ds_read_b128 v[126:129], v165 offset:42048
	ds_read_b128 v[142:145], v165 offset:50496
	ds_read_b128 v[146:149], v165 offset:58944
	ds_read_b128 v[168:171], v166 offset:42048
	s_waitcnt lgkmcnt(3)
	v_mfma_f32_16x16x32_bf16 v[130:133], v[220:223], v[126:129], v[130:133]
	s_waitcnt lgkmcnt(2)
	v_mfma_f32_16x16x32_bf16 v[134:137], v[220:223], v[142:145], v[134:137]
	s_waitcnt lgkmcnt(1)
	v_mfma_f32_16x16x32_bf16 v[138:141], v[220:223], v[146:149], v[138:141]
	s_waitcnt lgkmcnt(0)
	v_mfma_f32_16x16x32_bf16 v[84:87], v[220:223], v[168:171], v[88:91]
	s_waitcnt vmcnt(14)
	v_mfma_f32_16x16x32_bf16 v[88:91], v[228:231], v[126:129], v[96:99]
	v_mfma_f32_16x16x32_bf16 v[96:99], v[228:231], v[142:145], v[100:103]
	v_mfma_f32_16x16x32_bf16 v[100:103], v[228:231], v[146:149], v[122:125]
	v_mfma_f32_16x16x32_bf16 v[80:83], v[228:231], v[168:171], v[92:95]
	s_nop 2
	ds_read_b128 v[92:95], v165 offset:42112
	ds_read_b128 v[122:125], v165 offset:50560
	ds_read_b128 v[126:129], v165 offset:59008
	ds_read_b128 v[142:145], v166 offset:42112
	s_waitcnt vmcnt(13) lgkmcnt(3)
	v_mfma_f32_16x16x32_bf16 v[130:133], v[232:235], v[92:95], v[130:133]
	s_waitcnt lgkmcnt(2)
	v_mfma_f32_16x16x32_bf16 v[134:137], v[232:235], v[122:125], v[134:137]
	s_waitcnt lgkmcnt(1)
	v_mfma_f32_16x16x32_bf16 v[138:141], v[232:235], v[126:129], v[138:141]
	s_waitcnt lgkmcnt(0)
	v_mfma_f32_16x16x32_bf16 v[76:79], v[232:235], v[142:145], v[84:87]
	s_waitcnt vmcnt(11)
	v_mfma_f32_16x16x32_bf16 v[84:87], v[244:247], v[92:95], v[88:91]
	v_mfma_f32_16x16x32_bf16 v[88:91], v[244:247], v[122:125], v[96:99]
	v_mfma_f32_16x16x32_bf16 v[92:95], v[244:247], v[126:129], v[100:103]
	v_mfma_f32_16x16x32_bf16 v[72:75], v[244:247], v[142:145], v[80:83]
	s_nop 2
	ds_read_b128 v[80:83], v165 offset:42176
	ds_read_b128 v[96:99], v165 offset:50624
	ds_read_b128 v[100:103], v165 offset:59072
	ds_read_b128 v[122:125], v166 offset:42176
	s_waitcnt lgkmcnt(3)
	v_mfma_f32_16x16x32_bf16 v[126:129], v[236:239], v[80:83], v[130:133]
	s_waitcnt lgkmcnt(2)
	v_mfma_f32_16x16x32_bf16 v[130:133], v[236:239], v[96:99], v[134:137]
	s_waitcnt lgkmcnt(1)
	v_mfma_f32_16x16x32_bf16 v[134:137], v[236:239], v[100:103], v[138:141]
	s_waitcnt lgkmcnt(0)
	v_mfma_f32_16x16x32_bf16 v[68:71], v[236:239], v[122:125], v[76:79]
	s_waitcnt vmcnt(10)
	v_mfma_f32_16x16x32_bf16 v[76:79], v[248:251], v[80:83], v[84:87]
	v_mfma_f32_16x16x32_bf16 v[80:83], v[248:251], v[96:99], v[88:91]
	v_mfma_f32_16x16x32_bf16 v[84:87], v[248:251], v[100:103], v[92:95]
	v_mfma_f32_16x16x32_bf16 v[64:67], v[248:251], v[122:125], v[72:75]
	s_nop 2
	ds_read_b128 v[72:75], v165 offset:42240
	ds_read_b128 v[88:91], v165 offset:50688
	ds_read_b128 v[92:95], v165 offset:59136
	ds_read_b128 v[96:99], v166 offset:42240
	s_waitcnt vmcnt(9) lgkmcnt(3)
	v_mfma_f32_16x16x32_bf16 v[100:103], v[252:255], v[72:75], v[126:129]
	s_waitcnt lgkmcnt(2)
	v_mfma_f32_16x16x32_bf16 v[122:125], v[252:255], v[88:91], v[130:133]
	s_waitcnt lgkmcnt(1)
	v_mfma_f32_16x16x32_bf16 v[126:129], v[252:255], v[92:95], v[134:137]
	s_waitcnt lgkmcnt(0)
	v_mfma_f32_16x16x32_bf16 v[60:63], v[252:255], v[96:99], v[68:71]
	s_waitcnt vmcnt(7)
	v_mfma_f32_16x16x32_bf16 v[68:71], v[56:59], v[72:75], v[76:79]
	v_mfma_f32_16x16x32_bf16 v[72:75], v[56:59], v[88:91], v[80:83]
	v_mfma_f32_16x16x32_bf16 v[76:79], v[56:59], v[92:95], v[84:87]
	v_mfma_f32_16x16x32_bf16 v[56:59], v[56:59], v[96:99], v[64:67]
	s_nop 2
	ds_read_b128 v[64:67], v165 offset:42304
	ds_read_b128 v[80:83], v165 offset:50752
	ds_read_b128 v[84:87], v165 offset:59200
	ds_read_b128 v[88:91], v166 offset:42304
	s_waitcnt lgkmcnt(3)
	v_mfma_f32_16x16x32_bf16 v[92:95], v[48:51], v[64:67], v[100:103]
	s_waitcnt lgkmcnt(2)
	v_mfma_f32_16x16x32_bf16 v[96:99], v[48:51], v[80:83], v[122:125]
	s_waitcnt lgkmcnt(1)
	v_mfma_f32_16x16x32_bf16 v[100:103], v[48:51], v[84:87], v[126:129]
	s_waitcnt lgkmcnt(0)
	v_mfma_f32_16x16x32_bf16 v[48:51], v[48:51], v[88:91], v[60:63]
	s_waitcnt vmcnt(6)
	v_mfma_f32_16x16x32_bf16 v[60:63], v[44:47], v[64:67], v[68:71]
	v_mfma_f32_16x16x32_bf16 v[64:67], v[44:47], v[80:83], v[72:75]
	v_mfma_f32_16x16x32_bf16 v[68:71], v[44:47], v[84:87], v[76:79]
	v_mfma_f32_16x16x32_bf16 v[44:47], v[44:47], v[88:91], v[56:59]
	s_nop 2
	ds_read_b128 v[56:59], v165 offset:42368
	ds_read_b128 v[72:75], v165 offset:50816
	ds_read_b128 v[76:79], v165 offset:59264
	ds_read_b128 v[80:83], v166 offset:42368
	s_waitcnt vmcnt(5) lgkmcnt(3)
	v_mfma_f32_16x16x32_bf16 v[84:87], v[40:43], v[56:59], v[92:95]
	s_waitcnt lgkmcnt(2)
	v_mfma_f32_16x16x32_bf16 v[88:91], v[40:43], v[72:75], v[96:99]
	s_waitcnt lgkmcnt(1)
	v_mfma_f32_16x16x32_bf16 v[92:95], v[40:43], v[76:79], v[100:103]
	s_waitcnt lgkmcnt(0)
; __device__ __forceinline__ unsigned cvt_pk_bf16(float lo, float hi) { unsigned r; asm volatile("v_cvt_pk_bf16_f32 %0, %1, %2" : "=v"(r) : "v"(lo), "v"(hi)); return r; }
; #define LAS __attribute__((address_space(3)))
; #define MFMA16(a, b, c) __builtin_amdgcn_mfma_f32_16x16x32_bf16((a), (b), (c), 0, 0, 0)
; __device__ __forceinline__ void pool_units(LAS unsigned char* lds, const bf16* Z, const float* state, const bf16* Wpt, const float* pscale, bf16* MIXIN, int bx, int G, int tid, int wid, int lane) {
;     ...
;             for (int m = 0; m < 4; ++m) db[m] = *(const LAS bf16x8*)(Dl + (m * 16 + fr) * PL_DS + ks * 32 + fq * 8);
; #pragma unroll
;             for (int nt = 0; nt < 2; ++nt)
; #pragma unroll
;                 for (int m = 0; m < 4; ++m) acc[nt][m] = MFMA16(wa[ks][nt], db[m], acc[nt][m]);
;         }
; #pragma unroll
;         for (int nt = 0; nt < 2; ++nt) { const int col = g * 256 + 32 * wid + 16 * nt + fq * 4; const f32x4 ps = psc[nt];
; #pragma unroll
;             for (int m = 0; m < 4; ++m) { const f32x4 y = acc[nt][m] * ps; v2u o; o.x = pg8::cvt_pk_bf16(y.x, y.y); o.y = pg8::cvt_pk_bf16(y.z, y.w);
;                 *(v2u*)(MIXIN + (size_t)(row0 + m * 16 + fr) * DM + col) = o; } }
	v_mfma_f32_16x16x32_bf16 v[40:43], v[40:43], v[80:83], v[48:51]
	s_waitcnt vmcnt(3)
	v_mfma_f32_16x16x32_bf16 v[48:51], v[36:39], v[56:59], v[60:63]
	v_mfma_f32_16x16x32_bf16 v[56:59], v[36:39], v[72:75], v[64:67]
	v_mfma_f32_16x16x32_bf16 v[60:63], v[36:39], v[76:79], v[68:71]
	v_mfma_f32_16x16x32_bf16 v[36:39], v[36:39], v[80:83], v[44:47]
	s_nop 2
	ds_read_b128 v[44:47], v165 offset:42432
	ds_read_b128 v[64:67], v165 offset:50880
	ds_read_b128 v[68:71], v165 offset:59328
	ds_read_b128 v[72:75], v166 offset:42432
	s_waitcnt lgkmcnt(3)
	v_mfma_f32_16x16x32_bf16 v[76:79], v[32:35], v[44:47], v[84:87]
	s_waitcnt lgkmcnt(2)
	v_mfma_f32_16x16x32_bf16 v[80:83], v[32:35], v[64:67], v[88:91]
	s_waitcnt lgkmcnt(1)
	v_mfma_f32_16x16x32_bf16 v[84:87], v[32:35], v[68:71], v[92:95]
	s_waitcnt lgkmcnt(0)
	v_mfma_f32_16x16x32_bf16 v[32:35], v[32:35], v[72:75], v[40:43]
	s_waitcnt vmcnt(2)
	v_mfma_f32_16x16x32_bf16 v[40:43], v[28:31], v[44:47], v[48:51]
	v_mfma_f32_16x16x32_bf16 v[44:47], v[28:31], v[64:67], v[56:59]
	v_mfma_f32_16x16x32_bf16 v[48:51], v[28:31], v[68:71], v[60:63]
	s_waitcnt vmcnt(1)
	s_nop 0
	v_pk_mul_f32 v[56:57], v[24:25], v[76:77]
	v_pk_mul_f32 v[58:59], v[24:25], v[80:81]
	v_cvt_pk_bf16_f32 v56, v56, v57
	v_mfma_f32_16x16x32_bf16 v[28:31], v[28:31], v[72:75], v[36:39]
	v_mul_f32_e64 v60, v24, v84
	v_mul_f32_e64 v61, v25, v85
	v_pk_mul_f32 v[24:25], v[24:25], v[32:33]
	v_or_b32_e32 v36, s39, v109
	v_pk_mul_f32 v[38:39], v[26:27], v[78:79]
	v_ashrrev_i32_e32 v37, 31, v36
	v_cvt_pk_bf16_f32 v57, v38, v39
	v_lshlrev_b64 v[38:39], 12, v[36:37]
	v_lshl_add_u64 v[38:39], v[2:3], 0, v[38:39]
	global_store_dwordx2 v[38:39], v[56:57], off
	v_pk_mul_f32 v[56:57], v[26:27], v[82:83]
	v_cvt_pk_bf16_f32 v58, v58, v59
	s_nop 0
	v_cvt_pk_bf16_f32 v59, v56, v57
	v_or_b32_e32 v56, 16, v36
	v_ashrrev_i32_e32 v57, 31, v56
	v_lshlrev_b64 v[56:57], 12, v[56:57]
	v_lshl_add_u64 v[56:57], v[2:3], 0, v[56:57]
	global_store_dwordx2 v[56:57], v[58:59], off
	v_pk_mul_f32 v[58:59], v[26:27], v[86:87]
	v_cvt_pk_bf16_f32 v60, v60, v61
	v_pk_mul_f32 v[26:27], v[26:27], v[34:35]
	v_cvt_pk_bf16_f32 v61, v58, v59
	v_or_b32_e32 v58, 32, v36
	v_ashrrev_i32_e32 v59, 31, v58
	v_lshlrev_b64 v[58:59], 12, v[58:59]
	v_lshl_add_u64 v[58:59], v[2:3], 0, v[58:59]
	global_store_dwordx2 v[58:59], v[60:61], off
	v_cvt_pk_bf16_f32 v24, v24, v25
	v_cvt_pk_bf16_f32 v25, v26, v27
	v_or_b32_e32 v26, 48, v36
	v_ashrrev_i32_e32 v27, 31, v26
	v_lshlrev_b64 v[26:27], 12, v[26:27]
	v_lshl_add_u64 v[2:3], v[2:3], 0, v[26:27]
	s_waitcnt vmcnt(3)
	v_pk_mul_f32 v[26:27], v[16:17], v[40:41]
	global_store_dwordx2 v[2:3], v[24:25], off
	v_pk_mul_f32 v[24:25], v[18:19], v[42:43]
	v_cvt_pk_bf16_f32 v26, v26, v27
	s_nop 0
	v_cvt_pk_bf16_f32 v27, v24, v25
	global_store_dwordx2 v[38:39], v[26:27], off offset:32
	v_pk_mul_f32 v[26:27], v[16:17], v[44:45]
	v_pk_mul_f32 v[24:25], v[18:19], v[46:47]
	v_cvt_pk_bf16_f32 v26, v26, v27
	s_nop 0
	v_cvt_pk_bf16_f32 v27, v24, v25
	global_store_dwordx2 v[56:57], v[26:27], off offset:32
	v_pk_mul_f32 v[26:27], v[16:17], v[48:49]
	v_pk_mul_f32 v[16:17], v[16:17], v[28:29]
	v_pk_mul_f32 v[24:25], v[18:19], v[50:51]
	v_cvt_pk_bf16_f32 v26, v26, v27
	v_pk_mul_f32 v[18:19], v[18:19], v[30:31]
	v_cvt_pk_bf16_f32 v27, v24, v25
	global_store_dwordx2 v[58:59], v[26:27], off offset:32
	v_cvt_pk_bf16_f32 v16, v16, v17
	v_cvt_pk_bf16_f32 v17, v18, v19
	global_store_dwordx2 v[2:3], v[16:17], off offset:32
	s_cbranch_vccz .LBB0_169
; #define LAS __attribute__((address_space(3)))
; __device__ __forceinline__ unsigned pk2(float lo, float hi) { return f2bf(lo) | (f2bf(hi) << 16); }
; __device__ __forceinline__ v4u pool_load_piece(const bf16* Z, const float* state, int idx, int g, int rr, int cgx) {
;     const bool sample = idx >= 256; const int c = idx & 31; const int row0 = idx * 64; const int ch = g * 256 + cgx * 8;
;     v4u o = {0u, 0u, 0u, 0u};
;     if (rr >= 0 || (!sample && c > 0)) o = *(const v4u*)(Z + (size_t)(row0 + rr) * DIN + ch);
;     else if (sample) { const float* sp = state + ((size_t)(idx - 256) * 15 + (15 + rr)) * DPOOL + ch; const f32x4 a0 = *(const f32x4*)sp, a1 = *(const f32x4*)(sp + 4);
;         o.x = pk2(a0.x, a0.y); o.y = pk2(a0.z, a0.w); o.z = pk2(a1.x, a1.y); o.w = pk2(a1.z, a1.w); }
; __device__ __forceinline__ void pool_units(LAS unsigned char* lds, const bf16* Z, const float* state, const bf16* Wpt, const float* pscale, bf16* MIXIN, int bx, int G, int tid, int wid, int lane) {
;     ...
;         { const int rb = tid >> 5, cgx = tid & 31;
;           *(LAS v4u*)(Ul + rb * PL_DS + cgx * 8) = R.c0; *(LAS v4u*)(Ul + (rb + 16) * PL_DS + cgx * 8) = R.c1; *(LAS v4u*)(Ul + (rb + 32) * PL_DS + cgx * 8) = R.c2;
;           *(LAS v4u*)(Ul + (rb + 48) * PL_DS + cgx * 8) = R.c3; if (rb + 64 < 79) *(LAS v4u*)(Ul + (rb + 64) * PL_DS + cgx * 8) = R.c4; }
;         const int fr = lane & 15, fq = lane >> 4;
;         const bf16* wb = Wpt + (size_t)g * 65536 + (size_t)(32 * wid + fr) * 256 + fq * 8;
;         bf16x8 wa[8][2];
; #pragma unroll
;         for (int ks = 0; ks < 8; ++ks)
; #pragma unroll
;             for (int nt = 0; nt < 2; ++nt) wa[ks][nt] = *(const bf16x8*)(wb + nt * 16 * 256 + ks * 32);
;         f32x4 psc[2];
; #pragma unroll
;         for (int nt = 0; nt < 2; ++nt) psc[nt] = *(const f32x4*)(pscale + g * 256 + 32 * wid + 16 * nt + fq * 4);
;         __syncthreads();
;         if (u + G < NATT) pool_load(R, Z, state, (u + G) >> 2, (u + G) & 3, tid);
.Lpool_head2:
	s_waitcnt vmcnt(0)
	ds_write_b128 v108, v[4:7]
	ds_write_b128 v108, v[8:11] offset:8448
	ds_write_b128 v108, v[12:15] offset:16896
	ds_write_b128 v108, v[20:23] offset:25344
	s_and_saveexec_b64 s[38:39], s[40:41]
	ds_write_b128 v108, v[52:55] offset:33792
	s_or_b64 exec, exec, s[38:39]
	s_and_b32 s5, s4, 3
	s_lshl_b32 s88, s5, 17
	v_lshl_add_u64 v[2:3], v[110:111], 0, s[88:89]
	v_add_co_u32_e32 v16, vcc, 0x2000, v2
	s_lshl_b32 s88, s5, 10
	s_nop 0
	v_addc_co_u32_e32 v17, vcc, 0, v3, vcc
	global_load_dwordx4 v[48:51], v[2:3], off offset:320
	global_load_dwordx4 v[56:59], v[16:17], off offset:256
	global_load_dwordx4 v[44:47], v[16:17], off offset:320
	global_load_dwordx4 v[40:43], v[2:3], off offset:384
	global_load_dwordx4 v[32:35], v[2:3], off offset:448
	global_load_dwordx4 v[36:39], v[16:17], off offset:384
	global_load_dwordx4 v[28:31], v[16:17], off offset:448
	v_lshl_add_u64 v[2:3], v[112:113], 0, s[88:89]
	global_load_dwordx4 v[24:27], v[2:3], off
	global_load_dwordx4 v[16:19], v[2:3], off offset:64
	s_branch .Lpool_join
.LBB0_125:
	s_waitcnt vmcnt(0)
	ds_write_b128 v108, v[4:7]
	ds_write_b128 v108, v[8:11] offset:8448
	ds_write_b128 v108, v[12:15] offset:16896
	ds_write_b128 v108, v[20:23] offset:25344
	s_and_saveexec_b64 s[38:39], s[40:41]
	ds_write_b128 v108, v[52:55] offset:33792
	s_or_b64 exec, exec, s[38:39]
	s_and_b32 s5, s4, 3
	s_lshl_b32 s88, s5, 17
	v_lshl_add_u64 v[2:3], v[110:111], 0, s[88:89]
	v_add_co_u32_e32 v16, vcc, 0x2000, v2
	s_lshl_b32 s88, s5, 10
	s_nop 0
	v_addc_co_u32_e32 v17, vcc, 0, v3, vcc
	global_load_dwordx4 v[216:219], v[2:3], off
	global_load_dwordx4 v[220:223], v[2:3], off offset:64
	global_load_dwordx4 v[224:227], v[16:17], off
	global_load_dwordx4 v[228:231], v[16:17], off offset:64
	global_load_dwordx4 v[232:235], v[2:3], off offset:128
	global_load_dwordx4 v[236:239], v[2:3], off offset:192
	global_load_dwordx4 v[244:247], v[16:17], off offset:128
	global_load_dwordx4 v[248:251], v[16:17], off offset:192
	global_load_dwordx4 v[252:255], v[2:3], off offset:256
	global_load_dwordx4 v[48:51], v[2:3], off offset:320
	global_load_dwordx4 v[56:59], v[16:17], off offset:256
	global_load_dwordx4 v[44:47], v[16:17], off offset:320
	global_load_dwordx4 v[40:43], v[2:3], off offset:384
	global_load_dwordx4 v[32:35], v[2:3], off offset:448
	global_load_dwordx4 v[36:39], v[16:17], off offset:384
	global_load_dwordx4 v[28:31], v[16:17], off offset:448
	v_lshl_add_u64 v[2:3], v[112:113], 0, s[88:89]
	global_load_dwordx4 v[24:27], v[2:3], off
	global_load_dwordx4 v[16:19], v[2:3], off offset:64
.Lpool_join:
	s_add_i32 s61, s4, s3
	s_cmpk_gt_i32 s61, 0x47f
	s_cselect_b64 s[96:97], -1, 0
	s_and_b64 vcc, exec, s[96:97]
	s_waitcnt lgkmcnt(0)
	s_barrier
	s_cbranch_vccnz .LBB0_124
	s_ashr_i32 s12, s61, 2
	s_cmpk_lt_i32 s12, 0x100
	s_cselect_b64 s[82:83], -1, 0
	s_cmpk_gt_i32 s12, 0xff
	s_cselect_b64 s[50:51], -1, 0
	s_and_b32 s13, s11, 0x300
	v_or_b32_e32 v96, s13, v107
	s_mov_b64 s[52:53], s[26:27]
	s_and_saveexec_b64 s[38:39], s[40:41]
	s_cbranch_execz .LBB0_132
	s_and_b32 s13, s61, 0x7c
	s_cmp_eq_u32 s13, 0
	s_cselect_b64 s[62:63], -1, 0
	s_xor_b64 s[64:65], s[82:83], -1
	s_or_b64 s[62:63], s[64:65], s[62:63]
	s_mov_b64 s[52:53], -1
	s_and_b64 vcc, exec, s[62:63]
	s_cbranch_vccz .LBB0_162
	s_andn2_b64 vcc, exec, s[50:51]
	s_cbranch_vccnz .LBB0_161
	s_add_i32 s13, s12, 0xffffff00
	v_mad_u64_u32 v[2:3], s[52:53], s13, 15, v[104:105]
	v_lshlrev_b64 v[2:3], 12, v[2:3]
	v_lshl_add_u64 v[2:3], s[24:25], 0, v[2:3]
	v_lshlrev_b32_e32 v0, 2, v96
	v_lshl_add_u64 v[6:7], v[2:3], 0, v[0:1]
	global_load_dwordx4 v[2:5], v[6:7], off
	s_nop 0
	global_load_dwordx4 v[6:9], v[6:7], off offset:16
	s_mov_b64 s[52:53], 0
	s_waitcnt vmcnt(1)
	v_bfe_u32 v0, v2, 16, 1
	v_bfe_u32 v10, v3, 16, 1
	v_bfe_u32 v11, v4, 16, 1
	s_waitcnt vmcnt(0)
	v_bfe_u32 v13, v6, 16, 1
	v_bfe_u32 v14, v7, 16, 1
	v_bfe_u32 v15, v8, 16, 1
	v_bfe_u32 v12, v5, 16, 1
	v_bfe_u32 v20, v9, 16, 1
	v_add3_u32 v0, v2, v0, s84
	v_add3_u32 v2, v3, v10, s84
	v_add3_u32 v3, v4, v11, s84
	v_add3_u32 v4, v6, v13, s84
	v_add3_u32 v6, v7, v14, s84
	v_add3_u32 v7, v8, v15, s84
	v_add3_u32 v5, v5, v12, s84
	v_add3_u32 v8, v9, v20, s84
	v_lshrrev_b32_e32 v0, 16, v0
	v_lshrrev_b32_e32 v3, 16, v3
	v_lshrrev_b32_e32 v9, 16, v4
	v_lshrrev_b32_e32 v7, 16, v7
	v_and_or_b32 v4, v2, s85, v0
	v_and_or_b32 v5, v5, s85, v3
	v_and_or_b32 v6, v6, s85, v9
	v_and_or_b32 v7, v8, s85, v7
	s_branch .LBB0_162

; __global__ void __launch_bounds__(NTHREADS, 2) hymba_fwd(Args a_unused) {
;     extern __shared__ __attribute__((aligned(16))) unsigned char lds_raw[];
	.amdhsa_kernel _Z9hymba_fwd4Args
		.amdhsa_group_segment_fixed_size 0
		.amdhsa_private_segment_fixed_size 0
		.amdhsa_kernarg_size 416
		.amdhsa_user_sgpr_count 2
		.amdhsa_user_sgpr_dispatch_ptr 0
		.amdhsa_user_sgpr_queue_ptr 0
		.amdhsa_user_sgpr_kernarg_segment_ptr 1
		.amdhsa_user_sgpr_dispatch_id 0
		.amdhsa_user_sgpr_kernarg_preload_length 0
		.amdhsa_user_sgpr_kernarg_preload_offset 0
		.amdhsa_user_sgpr_private_segment_size 0
		.amdhsa_uses_dynamic_stack 0
		.amdhsa_enable_private_segment 0
		.amdhsa_system_sgpr_workgroup_id_x 1
		.amdhsa_system_sgpr_workgroup_id_y 0
		.amdhsa_system_sgpr_workgroup_id_z 0
		.amdhsa_system_sgpr_workgroup_info 0
		.amdhsa_system_vgpr_workitem_id 2
		.amdhsa_next_free_vgpr 256
		.amdhsa_next_free_sgpr 100
		.amdhsa_accum_offset 256
		.amdhsa_reserve_vcc 1
		.amdhsa_float_round_mode_32 0
		.amdhsa_float_round_mode_16_64 0
		.amdhsa_float_denorm_mode_32 3
		.amdhsa_float_denorm_mode_16_64 3
		.amdhsa_dx10_clamp 1
		.amdhsa_ieee_mode 1
		.amdhsa_fp16_overflow 0
		.amdhsa_tg_split 0
		.amdhsa_exception_fp_ieee_invalid_op 0
		.amdhsa_exception_fp_denorm_src 0
		.amdhsa_exception_fp_ieee_div_zero 0
		.amdhsa_exception_fp_ieee_overflow 0
		.amdhsa_exception_fp_ieee_underflow 0
		.amdhsa_exception_fp_ieee_inexact 0
		.amdhsa_exception_int_div_zero 0
	.end_amdhsa_kernel

; __global__ void __launch_bounds__(NTHREADS, 2) hymba_fwd(Args a_unused) {
;     extern __shared__ __attribute__((aligned(16))) unsigned char lds_raw[];
amdhsa.kernels:
  - .agpr_count:     0
    .args:
      - .offset:         0
        .size:           160
        .value_kind:     by_value
      - .offset:         160
        .size:           4
        .value_kind:     hidden_block_count_x
      - .offset:         164
        .size:           4
        .value_kind:     hidden_block_count_y
      - .offset:         168
        .size:           4
        .value_kind:     hidden_block_count_z
      - .offset:         172
        .size:           2
        .value_kind:     hidden_group_size_x
      - .offset:         174
        .size:           2
        .value_kind:     hidden_group_size_y
      - .offset:         176
        .size:           2
        .value_kind:     hidden_group_size_z
      - .offset:         178
        .size:           2
        .value_kind:     hidden_remainder_x
      - .offset:         180
        .size:           2
        .value_kind:     hidden_remainder_y
      - .offset:         182
        .size:           2
        .value_kind:     hidden_remainder_z
      - .offset:         200
        .size:           8
        .value_kind:     hidden_global_offset_x
      - .offset:         208
        .size:           8
        .value_kind:     hidden_global_offset_y
      - .offset:         216
        .size:           8
        .value_kind:     hidden_global_offset_z
      - .offset:         224
        .size:           2
        .value_kind:     hidden_grid_dims
      - .offset:         248
        .size:           8
        .value_kind:     hidden_multigrid_sync_arg
      - .offset:         280
        .size:           4
        .value_kind:     hidden_dynamic_lds_size
    .group_segment_fixed_size: 0
    .kernarg_segment_align: 8
    .kernarg_segment_size: 416
    .language:       OpenCL C
    .language_version:
      - 2
      - 0
    .max_flat_workgroup_size: 512
    .name:           _Z9hymba_fwd4Args
    .private_segment_fixed_size: 0
    .sgpr_count:     106
    .sgpr_spill_count: 74
    .symbol:         _Z9hymba_fwd4Args.kd
    .uniform_work_group_size: 1
    .uses_dynamic_stack: false
    .vgpr_count:     256
    .vgpr_spill_count: 0
    .wavefront_size: 64
